# v20 + Resid epilogue: each row pair's four H-tile loads issued one row earlier into dead registers (counted vmcnt, statically checked)
# baseline (speedup 1.0000x reference)
.LBB0_693:
.LBB0_694:
	v_or_b32_e32 v172, 32, v200
	v_ashrrev_i32_e32 v173, 31, v172
	v_lshlrev_b64 v[172:173], 11, v[172:173]
	v_lshl_add_u64 v[168:169], v[210:211], 0, v[172:173]
	v_or_b32_e32 v172, 48, v200
	v_ashrrev_i32_e32 v173, 31, v172
	v_lshlrev_b64 v[172:173], 11, v[172:173]
	v_lshl_add_u64 v[170:171], v[210:211], 0, v[172:173]
	global_load_dwordx4 v[178:181], v[168:169], off
	global_load_dwordx4 v[230:233], v[168:169], off offset:256
	global_load_dwordx4 v[240:243], v[170:171], off
	global_load_dwordx4 v[216:219], v[170:171], off offset:256
	s_waitcnt vmcnt(5)
	v_lshlrev_b32_e32 v146, 16, v174
	s_waitcnt lgkmcnt(0)
	v_and_b32_e32 v147, 0xffff0000, v174
	v_lshlrev_b32_e32 v148, 16, v175
	v_and_b32_e32 v149, 0xffff0000, v175
	v_lshlrev_b32_e32 v150, 16, v176
	v_and_b32_e32 v151, 0xffff0000, v176
	v_lshlrev_b32_e32 v152, 16, v177
	v_and_b32_e32 v153, 0xffff0000, v177
	v_pk_mul_f32 v[146:147], v[90:91], v[146:147]
	v_pk_mul_f32 v[148:149], v[92:93], v[148:149]
	v_pk_mul_f32 v[150:151], v[94:95], v[150:151]
	v_pk_mul_f32 v[152:153], v[96:97], v[152:153]
	v_pk_fma_f32 v[144:145], v[144:145], v[206:207], v[148:149]
	v_pk_fma_f32 v[142:143], v[142:143], v[208:209], v[146:147]
	v_pk_fma_f32 v[140:141], v[140:141], v[202:203], v[152:153]
	v_pk_fma_f32 v[138:139], v[138:139], v[204:205], v[150:151]
	s_and_b64 vcc, exec, s[6:7]
	s_mov_b64 s[20:21], -1
	s_cbranch_vccnz .LBB0_696
	v_mov_b32_e32 v148, v143
	v_mov_b32_e32 v149, v139
	v_mov_b32_e32 v146, v142
	v_mov_b32_e32 v147, v138
	v_pk_mul_f32 v[148:149], v[148:149], v[148:149]
	v_mov_b32_e32 v150, v145
	v_mov_b32_e32 v151, v141
	v_pk_fma_f32 v[146:147], v[146:147], v[146:147], v[148:149]
	v_mov_b32_e32 v148, v144
	v_mov_b32_e32 v149, v140
	v_pk_mul_f32 v[150:151], v[150:151], v[150:151]
	v_pk_mul_f32 v[166:167], v[68:69], v[140:141]
	v_pk_fma_f32 v[148:149], v[148:149], v[148:149], v[150:151]
	v_pk_mul_f32 v[150:151], v[70:71], v[142:143]
	v_pk_add_f32 v[146:147], v[146:147], v[148:149]
	v_pk_mul_f32 v[152:153], v[66:67], v[138:139]
	v_add_f32_e32 v148, v146, v147
	v_pk_mul_f32 v[146:147], v[72:73], v[144:145]
	v_cvt_pk_bf16_f32 v150, v150, v151
	v_cvt_pk_bf16_f32 v151, v146, v147
	v_cvt_pk_bf16_f32 v152, v152, v153
	v_cvt_pk_bf16_f32 v153, v166, v167
	s_mov_b64 s[20:21], 0
	global_store_dwordx4 v[212:213], v[150:153], off

.LBB0_698:
	s_waitcnt vmcnt(4)
	s_nop 0
	v_lshlrev_b32_e32 v138, 16, v162
	v_and_b32_e32 v139, 0xffff0000, v162
	v_lshlrev_b32_e32 v140, 16, v163
	v_and_b32_e32 v141, 0xffff0000, v163
	v_lshlrev_b32_e32 v142, 16, v164
	v_and_b32_e32 v143, 0xffff0000, v164
	v_lshlrev_b32_e32 v144, 16, v165
	v_and_b32_e32 v145, 0xffff0000, v165
	v_pk_mul_f32 v[138:139], v[82:83], v[138:139]
	v_pk_mul_f32 v[140:141], v[84:85], v[140:141]
	v_pk_mul_f32 v[142:143], v[86:87], v[142:143]
	v_pk_mul_f32 v[144:145], v[88:89], v[144:145]
	v_pk_fma_f32 v[136:137], v[136:137], v[158:159], v[140:141]
	v_pk_fma_f32 v[134:135], v[134:135], v[160:161], v[138:139]
	v_pk_fma_f32 v[132:133], v[132:133], v[154:155], v[144:145]
	v_pk_fma_f32 v[130:131], v[130:131], v[156:157], v[142:143]
	s_and_b64 vcc, exec, s[6:7]
	s_mov_b64 s[20:21], -1
	s_cbranch_vccnz .LBB0_701
	v_mov_b32_e32 v140, v135
	v_mov_b32_e32 v141, v131
	v_mov_b32_e32 v138, v134
	v_mov_b32_e32 v139, v130
	v_pk_mul_f32 v[140:141], v[140:141], v[140:141]
	v_mov_b32_e32 v142, v137
	v_mov_b32_e32 v143, v133
	v_pk_fma_f32 v[138:139], v[138:139], v[138:139], v[140:141]
	v_mov_b32_e32 v140, v136
	v_mov_b32_e32 v141, v132
	v_pk_mul_f32 v[142:143], v[142:143], v[142:143]
	v_pk_mul_f32 v[144:145], v[60:61], v[132:133]
	v_pk_fma_f32 v[140:141], v[140:141], v[140:141], v[142:143]
	v_pk_mul_f32 v[142:143], v[64:65], v[136:137]
	v_pk_add_f32 v[138:139], v[138:139], v[140:141]
	v_pk_mul_f32 v[140:141], v[62:63], v[134:135]
	v_add_f32_e32 v138, v138, v139
	v_pk_mul_f32 v[150:151], v[58:59], v[130:131]
	v_add_f32_e32 v138, v138, v148
	v_cvt_pk_bf16_f32 v140, v140, v141
	v_cvt_pk_bf16_f32 v141, v142, v143
	v_cvt_pk_bf16_f32 v142, v150, v151
	v_cvt_pk_bf16_f32 v143, v144, v145
	global_store_dwordx4 v[212:213], v[140:143], off offset:256
	s_cbranch_execz .LBB0_702

.LBB0_705:
.LBB0_706:
	v_or_b32_e32 v148, 32, v200
	v_ashrrev_i32_e32 v149, 31, v148
	s_waitcnt lgkmcnt(0)
	v_lshlrev_b64 v[130:131], 11, v[148:149]
	v_lshl_add_u64 v[146:147], v[210:211], 0, v[130:131]
	v_or_b32_e32 v144, 48, v200
	v_ashrrev_i32_e32 v145, 31, v144
	v_lshlrev_b64 v[130:131], 11, v[144:145]
	v_lshl_add_u64 v[142:143], v[210:211], 0, v[130:131]
	s_and_b64 vcc, exec, s[6:7]
	s_mov_b64 s[20:21], -1
	s_waitcnt vmcnt(3)
	v_lshlrev_b32_e32 v162, 16, v178
	v_and_b32_e32 v163, 0xffff0000, v178
	v_lshlrev_b32_e32 v150, 16, v179
	v_and_b32_e32 v151, 0xffff0000, v179
	v_lshlrev_b32_e32 v164, 16, v180
	v_and_b32_e32 v165, 0xffff0000, v180
	v_lshlrev_b32_e32 v152, 16, v181
	v_and_b32_e32 v153, 0xffff0000, v181
	v_pk_mul_f32 v[162:163], v[90:91], v[162:163]
	v_pk_mul_f32 v[150:151], v[92:93], v[150:151]
	v_pk_mul_f32 v[164:165], v[94:95], v[164:165]
	v_pk_mul_f32 v[152:153], v[96:97], v[152:153]
	v_pk_fma_f32 v[128:129], v[128:129], v[206:207], v[150:151]
	v_pk_fma_f32 v[126:127], v[126:127], v[208:209], v[162:163]
	v_pk_fma_f32 v[124:125], v[124:125], v[202:203], v[152:153]
	v_pk_fma_f32 v[122:123], v[122:123], v[204:205], v[164:165]
	s_cbranch_vccnz .LBB0_708
	v_mov_b32_e32 v152, v127
	v_mov_b32_e32 v153, v123
	v_mov_b32_e32 v150, v126
	v_mov_b32_e32 v151, v122
	v_pk_mul_f32 v[152:153], v[152:153], v[152:153]
	v_mov_b32_e32 v162, v129
	v_mov_b32_e32 v163, v125
	v_pk_fma_f32 v[150:151], v[150:151], v[150:151], v[152:153]
	v_mov_b32_e32 v152, v128
	v_mov_b32_e32 v153, v124
	v_pk_mul_f32 v[162:163], v[162:163], v[162:163]
	v_pk_mul_f32 v[166:167], v[68:69], v[124:125]
	v_pk_fma_f32 v[152:153], v[152:153], v[152:153], v[162:163]
	v_pk_mul_f32 v[162:163], v[70:71], v[126:127]
	v_pk_add_f32 v[150:151], v[150:151], v[152:153]
	v_pk_mul_f32 v[152:153], v[72:73], v[128:129]
	v_pk_mul_f32 v[164:165], v[66:67], v[122:123]
	v_add_f32_e32 v150, v150, v151
	v_cvt_pk_bf16_f32 v162, v162, v163
	v_cvt_pk_bf16_f32 v163, v152, v153
	v_cvt_pk_bf16_f32 v164, v164, v165
	v_cvt_pk_bf16_f32 v165, v166, v167
	s_mov_b64 s[20:21], 0
	global_store_dwordx4 v[146:147], v[162:165], off

.LBB0_710:
	s_waitcnt vmcnt(2)
	s_nop 0
	v_lshlrev_b32_e32 v122, 16, v230
	v_and_b32_e32 v123, 0xffff0000, v230
	v_lshlrev_b32_e32 v124, 16, v231
	v_and_b32_e32 v125, 0xffff0000, v231
	v_lshlrev_b32_e32 v126, 16, v232
	v_and_b32_e32 v127, 0xffff0000, v232
	v_lshlrev_b32_e32 v128, 16, v233
	v_and_b32_e32 v129, 0xffff0000, v233
	v_pk_mul_f32 v[122:123], v[82:83], v[122:123]
	v_pk_mul_f32 v[124:125], v[84:85], v[124:125]
	v_pk_mul_f32 v[126:127], v[86:87], v[126:127]
	v_pk_mul_f32 v[128:129], v[88:89], v[128:129]
	v_pk_fma_f32 v[120:121], v[120:121], v[158:159], v[124:125]
	v_pk_fma_f32 v[118:119], v[118:119], v[160:161], v[122:123]
	v_pk_fma_f32 v[116:117], v[116:117], v[154:155], v[128:129]
	v_pk_fma_f32 v[114:115], v[114:115], v[156:157], v[126:127]
	s_and_b64 vcc, exec, s[6:7]
	s_mov_b64 s[20:21], -1
	s_cbranch_vccnz .LBB0_713
	v_mov_b32_e32 v124, v119
	v_mov_b32_e32 v125, v115
	v_mov_b32_e32 v122, v118
	v_mov_b32_e32 v123, v114
	v_pk_mul_f32 v[124:125], v[124:125], v[124:125]
	v_mov_b32_e32 v126, v121
	v_mov_b32_e32 v127, v117
	v_pk_fma_f32 v[122:123], v[122:123], v[122:123], v[124:125]
	v_mov_b32_e32 v124, v120
	v_mov_b32_e32 v125, v116
	v_pk_mul_f32 v[126:127], v[126:127], v[126:127]
	v_pk_mul_f32 v[128:129], v[60:61], v[116:117]
	v_pk_fma_f32 v[124:125], v[124:125], v[124:125], v[126:127]
	v_pk_mul_f32 v[126:127], v[64:65], v[120:121]
	v_pk_add_f32 v[122:123], v[122:123], v[124:125]
	v_pk_mul_f32 v[124:125], v[62:63], v[118:119]
	v_add_f32_e32 v122, v122, v123
	v_pk_mul_f32 v[138:139], v[58:59], v[114:115]
	v_add_f32_e32 v122, v122, v150
	v_cvt_pk_bf16_f32 v124, v124, v125
	v_cvt_pk_bf16_f32 v125, v126, v127
	v_cvt_pk_bf16_f32 v126, v138, v139
	v_cvt_pk_bf16_f32 v127, v128, v129
	global_store_dwordx4 v[146:147], v[124:127], off offset:256
	s_cbranch_execz .LBB0_714

.LBB0_717:
.LBB0_718:
	v_add_u32_e32 v170, 0x80, v200
	v_ashrrev_i32_e32 v171, 31, v170
	v_lshlrev_b64 v[170:171], 11, v[170:171]
	v_lshl_add_u64 v[166:167], v[210:211], 0, v[170:171]
	v_add_u32_e32 v170, 0x90, v200
	v_ashrrev_i32_e32 v171, 31, v170
	v_lshlrev_b64 v[170:171], 11, v[170:171]
	v_lshl_add_u64 v[168:169], v[210:211], 0, v[170:171]
	global_load_dwordx4 v[138:141], v[166:167], off
	global_load_dwordx4 v[146:149], v[166:167], off offset:256
	global_load_dwordx4 v[150:153], v[168:169], off
	global_load_dwordx4 v[162:165], v[168:169], off offset:256
	s_waitcnt vmcnt(5)
	v_lshlrev_b32_e32 v114, 16, v240
	s_waitcnt lgkmcnt(0)
	v_and_b32_e32 v115, 0xffff0000, v240
	v_lshlrev_b32_e32 v116, 16, v241
	v_and_b32_e32 v117, 0xffff0000, v241
	v_lshlrev_b32_e32 v118, 16, v242
	v_and_b32_e32 v119, 0xffff0000, v242
	v_lshlrev_b32_e32 v120, 16, v243
	v_and_b32_e32 v121, 0xffff0000, v243
	v_pk_mul_f32 v[114:115], v[90:91], v[114:115]
	v_pk_mul_f32 v[116:117], v[92:93], v[116:117]
	v_pk_mul_f32 v[118:119], v[94:95], v[118:119]
	v_pk_mul_f32 v[120:121], v[96:97], v[120:121]
	v_pk_fma_f32 v[112:113], v[112:113], v[206:207], v[116:117]
	v_pk_fma_f32 v[110:111], v[110:111], v[208:209], v[114:115]
	v_pk_fma_f32 v[108:109], v[108:109], v[202:203], v[120:121]
	v_pk_fma_f32 v[106:107], v[106:107], v[204:205], v[118:119]
	s_and_b64 vcc, exec, s[6:7]
	s_mov_b64 s[20:21], -1
	s_cbranch_vccnz .LBB0_720
	v_mov_b32_e32 v116, v111
	v_mov_b32_e32 v117, v107
	v_mov_b32_e32 v114, v110
	v_mov_b32_e32 v115, v106
	v_pk_mul_f32 v[116:117], v[116:117], v[116:117]
	v_mov_b32_e32 v118, v113
	v_mov_b32_e32 v119, v109
	v_pk_fma_f32 v[114:115], v[114:115], v[114:115], v[116:117]
	v_mov_b32_e32 v116, v112
	v_mov_b32_e32 v117, v108
	v_pk_mul_f32 v[118:119], v[118:119], v[118:119]
	v_pk_mul_f32 v[122:123], v[68:69], v[108:109]
	v_pk_fma_f32 v[116:117], v[116:117], v[116:117], v[118:119]
	v_pk_mul_f32 v[118:119], v[70:71], v[110:111]
	v_pk_add_f32 v[114:115], v[114:115], v[116:117]
	v_pk_mul_f32 v[120:121], v[66:67], v[106:107]
	v_add_f32_e32 v116, v114, v115
	v_pk_mul_f32 v[114:115], v[72:73], v[112:113]
	v_cvt_pk_bf16_f32 v118, v118, v119
	v_cvt_pk_bf16_f32 v119, v114, v115
	v_cvt_pk_bf16_f32 v120, v120, v121
	v_cvt_pk_bf16_f32 v121, v122, v123
	s_mov_b64 s[20:21], 0
	global_store_dwordx4 v[142:143], v[118:121], off

.LBB0_722:
	s_waitcnt vmcnt(4)
	s_nop 0
	v_lshlrev_b32_e32 v106, 16, v216
	v_and_b32_e32 v107, 0xffff0000, v216
	v_lshlrev_b32_e32 v108, 16, v217
	v_and_b32_e32 v109, 0xffff0000, v217
	v_lshlrev_b32_e32 v110, 16, v218
	v_and_b32_e32 v111, 0xffff0000, v218
	v_lshlrev_b32_e32 v112, 16, v219
	v_and_b32_e32 v113, 0xffff0000, v219
	v_pk_mul_f32 v[106:107], v[82:83], v[106:107]
	v_pk_mul_f32 v[108:109], v[84:85], v[108:109]
	v_pk_mul_f32 v[110:111], v[86:87], v[110:111]
	v_pk_mul_f32 v[112:113], v[88:89], v[112:113]
	v_pk_fma_f32 v[104:105], v[104:105], v[158:159], v[108:109]
	v_pk_fma_f32 v[102:103], v[102:103], v[160:161], v[106:107]
	v_pk_fma_f32 v[100:101], v[100:101], v[154:155], v[112:113]
	v_pk_fma_f32 v[98:99], v[98:99], v[156:157], v[110:111]
	s_and_b64 vcc, exec, s[6:7]
	s_mov_b64 s[20:21], -1
	s_cbranch_vccnz .LBB0_725
	v_mov_b32_e32 v108, v103
	v_mov_b32_e32 v109, v99
	v_mov_b32_e32 v106, v102
	v_mov_b32_e32 v107, v98
	v_pk_mul_f32 v[108:109], v[108:109], v[108:109]
	v_mov_b32_e32 v110, v105
	v_mov_b32_e32 v111, v101
	v_pk_fma_f32 v[106:107], v[106:107], v[106:107], v[108:109]
	v_mov_b32_e32 v108, v104
	v_mov_b32_e32 v109, v100
	v_pk_mul_f32 v[110:111], v[110:111], v[110:111]
	v_pk_mul_f32 v[112:113], v[60:61], v[100:101]
	v_pk_fma_f32 v[108:109], v[108:109], v[108:109], v[110:111]
	v_pk_mul_f32 v[110:111], v[64:65], v[104:105]
	v_pk_add_f32 v[106:107], v[106:107], v[108:109]
	v_pk_mul_f32 v[108:109], v[62:63], v[102:103]
	v_add_f32_e32 v106, v106, v107
	v_pk_mul_f32 v[118:119], v[58:59], v[98:99]
	v_add_f32_e32 v106, v106, v116
	v_cvt_pk_bf16_f32 v108, v108, v109
	v_cvt_pk_bf16_f32 v109, v110, v111
	v_cvt_pk_bf16_f32 v110, v118, v119
	v_cvt_pk_bf16_f32 v111, v112, v113
	global_store_dwordx4 v[142:143], v[108:111], off offset:256
	s_cbranch_execz .LBB0_726

.LBB0_729:
.LBB0_730:
	v_add_u32_e32 v116, 0x80, v200
	v_ashrrev_i32_e32 v117, 31, v116
	s_waitcnt lgkmcnt(0)
	v_lshlrev_b64 v[98:99], 11, v[116:117]
	v_lshl_add_u64 v[114:115], v[210:211], 0, v[98:99]
	v_add_u32_e32 v112, 0x90, v200
	v_ashrrev_i32_e32 v113, 31, v112
	v_lshlrev_b64 v[98:99], 11, v[112:113]
	v_lshl_add_u64 v[110:111], v[210:211], 0, v[98:99]
	s_and_b64 vcc, exec, s[6:7]
	s_mov_b64 s[20:21], -1
	s_waitcnt vmcnt(3)
	v_lshlrev_b32_e32 v122, 16, v138
	v_and_b32_e32 v123, 0xffff0000, v138
	v_lshlrev_b32_e32 v118, 16, v139
	v_and_b32_e32 v119, 0xffff0000, v139
	v_lshlrev_b32_e32 v124, 16, v140
	v_and_b32_e32 v125, 0xffff0000, v140
	v_lshlrev_b32_e32 v120, 16, v141
	v_and_b32_e32 v121, 0xffff0000, v141
	v_pk_mul_f32 v[122:123], v[90:91], v[122:123]
	v_pk_mul_f32 v[118:119], v[92:93], v[118:119]
	v_pk_mul_f32 v[124:125], v[94:95], v[124:125]
	v_pk_mul_f32 v[120:121], v[96:97], v[120:121]
	v_pk_fma_f32 v[80:81], v[80:81], v[206:207], v[118:119]
	v_pk_fma_f32 v[78:79], v[78:79], v[208:209], v[122:123]
	v_pk_fma_f32 v[76:77], v[76:77], v[202:203], v[120:121]
	v_pk_fma_f32 v[74:75], v[74:75], v[204:205], v[124:125]
	s_cbranch_vccnz .LBB0_732
	v_mov_b32_e32 v120, v79
	v_mov_b32_e32 v121, v75
	v_mov_b32_e32 v118, v78
	v_mov_b32_e32 v119, v74
	v_pk_mul_f32 v[120:121], v[120:121], v[120:121]
	v_mov_b32_e32 v122, v81
	v_mov_b32_e32 v123, v77
	v_pk_fma_f32 v[118:119], v[118:119], v[118:119], v[120:121]
	v_mov_b32_e32 v120, v80
	v_mov_b32_e32 v121, v76
	v_pk_mul_f32 v[122:123], v[122:123], v[122:123]
	v_pk_mul_f32 v[124:125], v[68:69], v[76:77]
	v_pk_fma_f32 v[120:121], v[120:121], v[120:121], v[122:123]
	v_pk_mul_f32 v[122:123], v[72:73], v[80:81]
	v_pk_add_f32 v[118:119], v[118:119], v[120:121]
	v_pk_mul_f32 v[120:121], v[70:71], v[78:79]
	v_pk_mul_f32 v[126:127], v[66:67], v[74:75]
	v_add_f32_e32 v118, v118, v119
	v_cvt_pk_bf16_f32 v120, v120, v121
	v_cvt_pk_bf16_f32 v121, v122, v123
	v_cvt_pk_bf16_f32 v122, v126, v127
	v_cvt_pk_bf16_f32 v123, v124, v125
	s_mov_b64 s[20:21], 0
	global_store_dwordx4 v[114:115], v[120:123], off

.LBB0_734:
	s_waitcnt vmcnt(2)
	s_nop 0
	v_lshlrev_b32_e32 v74, 16, v146
	v_and_b32_e32 v75, 0xffff0000, v146
	v_lshlrev_b32_e32 v76, 16, v147
	v_and_b32_e32 v77, 0xffff0000, v147
	v_lshlrev_b32_e32 v78, 16, v148
	v_and_b32_e32 v79, 0xffff0000, v148
	v_lshlrev_b32_e32 v80, 16, v149
	v_and_b32_e32 v81, 0xffff0000, v149
	v_pk_mul_f32 v[74:75], v[82:83], v[74:75]
	v_pk_mul_f32 v[76:77], v[84:85], v[76:77]
	v_pk_mul_f32 v[78:79], v[86:87], v[78:79]
	v_pk_mul_f32 v[80:81], v[88:89], v[80:81]
	v_pk_fma_f32 v[56:57], v[56:57], v[158:159], v[76:77]
	v_pk_fma_f32 v[54:55], v[54:55], v[160:161], v[74:75]
	v_pk_fma_f32 v[52:53], v[52:53], v[154:155], v[80:81]
	v_pk_fma_f32 v[50:51], v[50:51], v[156:157], v[78:79]
	s_and_b64 vcc, exec, s[6:7]
	s_mov_b64 s[20:21], -1
	s_cbranch_vccnz .LBB0_737
	v_mov_b32_e32 v76, v55
	v_mov_b32_e32 v77, v51
	v_mov_b32_e32 v74, v54
	v_mov_b32_e32 v75, v50
	v_pk_mul_f32 v[76:77], v[76:77], v[76:77]
	v_mov_b32_e32 v78, v57
	v_mov_b32_e32 v79, v53
	v_pk_fma_f32 v[74:75], v[74:75], v[74:75], v[76:77]
	v_mov_b32_e32 v76, v56
	v_mov_b32_e32 v77, v52
	v_pk_mul_f32 v[78:79], v[78:79], v[78:79]
	v_pk_mul_f32 v[80:81], v[60:61], v[52:53]
	v_pk_fma_f32 v[76:77], v[76:77], v[76:77], v[78:79]
	v_pk_mul_f32 v[78:79], v[64:65], v[56:57]
	v_pk_add_f32 v[74:75], v[74:75], v[76:77]
	v_pk_mul_f32 v[76:77], v[62:63], v[54:55]
	v_add_f32_e32 v74, v74, v75
	v_pk_mul_f32 v[106:107], v[58:59], v[50:51]
	v_add_f32_e32 v74, v74, v118
	v_cvt_pk_bf16_f32 v76, v76, v77
	v_cvt_pk_bf16_f32 v77, v78, v79
	v_cvt_pk_bf16_f32 v78, v106, v107
	v_cvt_pk_bf16_f32 v79, v80, v81
	global_store_dwordx4 v[114:115], v[76:79], off offset:256
	s_cbranch_execz .LBB0_738

.LBB0_741:
.LBB0_742:
	v_add_u32_e32 v134, 0xa0, v200
	v_ashrrev_i32_e32 v135, 31, v134
	v_lshlrev_b64 v[134:135], 11, v[134:135]
	v_lshl_add_u64 v[130:131], v[210:211], 0, v[134:135]
	v_add_u32_e32 v134, 0xb0, v200
	v_ashrrev_i32_e32 v135, 31, v134
	v_lshlrev_b64 v[134:135], 11, v[134:135]
	v_lshl_add_u64 v[132:133], v[210:211], 0, v[134:135]
	global_load_dwordx4 v[114:117], v[130:131], off
	global_load_dwordx4 v[118:121], v[130:131], off offset:256
	global_load_dwordx4 v[122:125], v[132:133], off
	global_load_dwordx4 v[126:129], v[132:133], off offset:256
	s_waitcnt vmcnt(5)
	v_lshlrev_b32_e32 v50, 16, v150
	s_waitcnt lgkmcnt(0)
	v_and_b32_e32 v51, 0xffff0000, v150
	v_lshlrev_b32_e32 v52, 16, v151
	v_and_b32_e32 v53, 0xffff0000, v151
	v_lshlrev_b32_e32 v54, 16, v152
	v_and_b32_e32 v55, 0xffff0000, v152
	v_lshlrev_b32_e32 v56, 16, v153
	v_and_b32_e32 v57, 0xffff0000, v153
	v_pk_mul_f32 v[50:51], v[90:91], v[50:51]
	v_pk_mul_f32 v[52:53], v[92:93], v[52:53]
	v_pk_mul_f32 v[54:55], v[94:95], v[54:55]
	v_pk_mul_f32 v[56:57], v[96:97], v[56:57]
	v_pk_fma_f32 v[48:49], v[48:49], v[206:207], v[52:53]
	v_pk_fma_f32 v[46:47], v[46:47], v[208:209], v[50:51]
	v_pk_fma_f32 v[44:45], v[44:45], v[202:203], v[56:57]
	v_pk_fma_f32 v[42:43], v[42:43], v[204:205], v[54:55]
	s_and_b64 vcc, exec, s[6:7]
	s_mov_b64 s[20:21], -1
	s_cbranch_vccnz .LBB0_744
	v_mov_b32_e32 v52, v47
	v_mov_b32_e32 v53, v43
	v_mov_b32_e32 v50, v46
	v_mov_b32_e32 v51, v42
	v_pk_mul_f32 v[52:53], v[52:53], v[52:53]
	v_mov_b32_e32 v54, v49
	v_mov_b32_e32 v55, v45
	v_pk_fma_f32 v[50:51], v[50:51], v[50:51], v[52:53]
	v_mov_b32_e32 v52, v48
	v_mov_b32_e32 v53, v44
	v_pk_mul_f32 v[54:55], v[54:55], v[54:55]
	v_pk_mul_f32 v[74:75], v[68:69], v[44:45]
	v_pk_fma_f32 v[52:53], v[52:53], v[52:53], v[54:55]
	v_pk_mul_f32 v[54:55], v[70:71], v[46:47]
	v_pk_add_f32 v[50:51], v[50:51], v[52:53]
	v_pk_mul_f32 v[56:57], v[66:67], v[42:43]
	v_add_f32_e32 v52, v50, v51
	v_pk_mul_f32 v[50:51], v[72:73], v[48:49]
	v_cvt_pk_bf16_f32 v54, v54, v55
	v_cvt_pk_bf16_f32 v55, v50, v51
	v_cvt_pk_bf16_f32 v56, v56, v57
	v_cvt_pk_bf16_f32 v57, v74, v75
	s_mov_b64 s[20:21], 0
	global_store_dwordx4 v[110:111], v[54:57], off

.LBB0_746:
	s_waitcnt vmcnt(4)
	s_nop 0
	v_lshlrev_b32_e32 v42, 16, v162
	v_and_b32_e32 v43, 0xffff0000, v162
	v_lshlrev_b32_e32 v44, 16, v163
	v_and_b32_e32 v45, 0xffff0000, v163
	v_lshlrev_b32_e32 v46, 16, v164
	v_and_b32_e32 v47, 0xffff0000, v164
	v_lshlrev_b32_e32 v48, 16, v165
	v_and_b32_e32 v49, 0xffff0000, v165
	v_pk_mul_f32 v[42:43], v[82:83], v[42:43]
	v_pk_mul_f32 v[44:45], v[84:85], v[44:45]
	v_pk_mul_f32 v[46:47], v[86:87], v[46:47]
	v_pk_mul_f32 v[48:49], v[88:89], v[48:49]
	v_pk_fma_f32 v[40:41], v[40:41], v[158:159], v[44:45]
	v_pk_fma_f32 v[38:39], v[38:39], v[160:161], v[42:43]
	v_pk_fma_f32 v[36:37], v[36:37], v[154:155], v[48:49]
	v_pk_fma_f32 v[34:35], v[34:35], v[156:157], v[46:47]
	s_and_b64 vcc, exec, s[6:7]
	s_mov_b64 s[20:21], -1
	s_cbranch_vccnz .LBB0_749
	v_mov_b32_e32 v44, v39
	v_mov_b32_e32 v45, v35
	v_mov_b32_e32 v42, v38
	v_mov_b32_e32 v43, v34
	v_pk_mul_f32 v[44:45], v[44:45], v[44:45]
	v_mov_b32_e32 v46, v41
	v_mov_b32_e32 v47, v37
	v_pk_fma_f32 v[42:43], v[42:43], v[42:43], v[44:45]
	v_mov_b32_e32 v44, v40
	v_mov_b32_e32 v45, v36
	v_pk_mul_f32 v[46:47], v[46:47], v[46:47]
	v_pk_mul_f32 v[48:49], v[60:61], v[36:37]
	v_pk_fma_f32 v[44:45], v[44:45], v[44:45], v[46:47]
	v_pk_mul_f32 v[46:47], v[64:65], v[40:41]
	v_pk_add_f32 v[42:43], v[42:43], v[44:45]
	v_pk_mul_f32 v[44:45], v[62:63], v[38:39]
	v_add_f32_e32 v42, v42, v43
	v_pk_mul_f32 v[54:55], v[58:59], v[34:35]
	v_add_f32_e32 v42, v42, v52
	v_cvt_pk_bf16_f32 v44, v44, v45
	v_cvt_pk_bf16_f32 v45, v46, v47
	v_cvt_pk_bf16_f32 v46, v54, v55
	v_cvt_pk_bf16_f32 v47, v48, v49
	global_store_dwordx4 v[110:111], v[44:47], off offset:256
	s_cbranch_execz .LBB0_750

.LBB0_753:
.LBB0_754:
	v_add_u32_e32 v52, 0xa0, v200
	v_ashrrev_i32_e32 v53, 31, v52
	s_waitcnt lgkmcnt(0)
	v_lshlrev_b64 v[34:35], 11, v[52:53]
	v_lshl_add_u64 v[50:51], v[210:211], 0, v[34:35]
	v_add_u32_e32 v48, 0xb0, v200
	v_ashrrev_i32_e32 v49, 31, v48
	v_lshlrev_b64 v[34:35], 11, v[48:49]
	v_lshl_add_u64 v[46:47], v[210:211], 0, v[34:35]
	s_and_b64 vcc, exec, s[6:7]
	s_mov_b64 s[20:21], -1
	s_waitcnt vmcnt(3)
	v_lshlrev_b32_e32 v74, 16, v114
	v_and_b32_e32 v75, 0xffff0000, v114
	v_lshlrev_b32_e32 v54, 16, v115
	v_and_b32_e32 v55, 0xffff0000, v115
	v_lshlrev_b32_e32 v76, 16, v116
	v_and_b32_e32 v77, 0xffff0000, v116
	v_lshlrev_b32_e32 v56, 16, v117
	v_and_b32_e32 v57, 0xffff0000, v117
	v_pk_mul_f32 v[74:75], v[90:91], v[74:75]
	v_pk_mul_f32 v[54:55], v[92:93], v[54:55]
	v_pk_mul_f32 v[76:77], v[94:95], v[76:77]
	v_pk_mul_f32 v[56:57], v[96:97], v[56:57]
	v_pk_fma_f32 v[32:33], v[32:33], v[206:207], v[54:55]
	v_pk_fma_f32 v[30:31], v[30:31], v[208:209], v[74:75]
	v_pk_fma_f32 v[28:29], v[28:29], v[202:203], v[56:57]
	v_pk_fma_f32 v[26:27], v[26:27], v[204:205], v[76:77]
	s_cbranch_vccnz .LBB0_756
	v_mov_b32_e32 v56, v31
	v_mov_b32_e32 v57, v27
	v_mov_b32_e32 v54, v30
	v_mov_b32_e32 v55, v26
	v_pk_mul_f32 v[56:57], v[56:57], v[56:57]
	v_mov_b32_e32 v74, v33
	v_mov_b32_e32 v75, v29
	v_pk_fma_f32 v[54:55], v[54:55], v[54:55], v[56:57]
	v_mov_b32_e32 v56, v32
	v_mov_b32_e32 v57, v28
	v_pk_mul_f32 v[74:75], v[74:75], v[74:75]
	v_pk_mul_f32 v[78:79], v[68:69], v[28:29]
	v_pk_fma_f32 v[56:57], v[56:57], v[56:57], v[74:75]
	v_pk_mul_f32 v[74:75], v[70:71], v[30:31]
	v_pk_add_f32 v[54:55], v[54:55], v[56:57]
	v_pk_mul_f32 v[56:57], v[72:73], v[32:33]
	v_pk_mul_f32 v[76:77], v[66:67], v[26:27]
	v_add_f32_e32 v54, v54, v55
	v_cvt_pk_bf16_f32 v74, v74, v75
	v_cvt_pk_bf16_f32 v75, v56, v57
	v_cvt_pk_bf16_f32 v76, v76, v77
	v_cvt_pk_bf16_f32 v77, v78, v79
	s_mov_b64 s[20:21], 0
	global_store_dwordx4 v[50:51], v[74:77], off

.LBB0_758:
	s_waitcnt vmcnt(2)
	s_nop 0
	v_lshlrev_b32_e32 v26, 16, v118
	v_and_b32_e32 v27, 0xffff0000, v118
	v_lshlrev_b32_e32 v28, 16, v119
	v_and_b32_e32 v29, 0xffff0000, v119
	v_lshlrev_b32_e32 v30, 16, v120
	v_and_b32_e32 v31, 0xffff0000, v120
	v_lshlrev_b32_e32 v32, 16, v121
	v_and_b32_e32 v33, 0xffff0000, v121
	v_pk_mul_f32 v[26:27], v[82:83], v[26:27]
	v_pk_mul_f32 v[28:29], v[84:85], v[28:29]
	v_pk_mul_f32 v[30:31], v[86:87], v[30:31]
	v_pk_mul_f32 v[32:33], v[88:89], v[32:33]
	v_pk_fma_f32 v[24:25], v[24:25], v[158:159], v[28:29]
	v_pk_fma_f32 v[22:23], v[22:23], v[160:161], v[26:27]
	v_pk_fma_f32 v[20:21], v[20:21], v[154:155], v[32:33]
	v_pk_fma_f32 v[18:19], v[18:19], v[156:157], v[30:31]
	s_and_b64 vcc, exec, s[6:7]
	s_mov_b64 s[20:21], -1
	s_cbranch_vccnz .LBB0_761
	v_mov_b32_e32 v28, v23
	v_mov_b32_e32 v29, v19
	v_mov_b32_e32 v26, v22
	v_mov_b32_e32 v27, v18
	v_pk_mul_f32 v[28:29], v[28:29], v[28:29]
	v_mov_b32_e32 v30, v25
	v_mov_b32_e32 v31, v21
	v_pk_fma_f32 v[26:27], v[26:27], v[26:27], v[28:29]
	v_mov_b32_e32 v28, v24
	v_mov_b32_e32 v29, v20
	v_pk_mul_f32 v[30:31], v[30:31], v[30:31]
	v_pk_mul_f32 v[32:33], v[60:61], v[20:21]
	v_pk_fma_f32 v[28:29], v[28:29], v[28:29], v[30:31]
	v_pk_mul_f32 v[30:31], v[64:65], v[24:25]
	v_pk_add_f32 v[26:27], v[26:27], v[28:29]
	v_pk_mul_f32 v[28:29], v[62:63], v[22:23]
	v_add_f32_e32 v26, v26, v27
	v_pk_mul_f32 v[42:43], v[58:59], v[18:19]
	v_add_f32_e32 v26, v26, v54
	v_cvt_pk_bf16_f32 v28, v28, v29
	v_cvt_pk_bf16_f32 v29, v30, v31
	v_cvt_pk_bf16_f32 v30, v42, v43
	v_cvt_pk_bf16_f32 v31, v32, v33
	global_store_dwordx4 v[50:51], v[28:31], off offset:256
	s_cbranch_execz .LBB0_762

.LBB0_765:
.LBB0_766:
	s_waitcnt vmcnt(1)
	v_lshlrev_b32_e32 v18, 16, v122
	s_waitcnt lgkmcnt(0)
	v_and_b32_e32 v19, 0xffff0000, v122
	v_lshlrev_b32_e32 v20, 16, v123
	v_and_b32_e32 v21, 0xffff0000, v123
	v_lshlrev_b32_e32 v22, 16, v124
	v_and_b32_e32 v23, 0xffff0000, v124
	v_lshlrev_b32_e32 v24, 16, v125
	v_and_b32_e32 v25, 0xffff0000, v125
	v_pk_mul_f32 v[18:19], v[90:91], v[18:19]
	v_pk_mul_f32 v[20:21], v[92:93], v[20:21]
	v_pk_mul_f32 v[22:23], v[94:95], v[22:23]
	v_pk_mul_f32 v[24:25], v[96:97], v[24:25]
	v_pk_fma_f32 v[16:17], v[16:17], v[206:207], v[20:21]
	v_pk_fma_f32 v[14:15], v[14:15], v[208:209], v[18:19]
	v_pk_fma_f32 v[12:13], v[12:13], v[202:203], v[24:25]
	v_pk_fma_f32 v[10:11], v[10:11], v[204:205], v[22:23]
	s_and_b64 vcc, exec, s[6:7]
	s_mov_b64 s[20:21], -1
	s_cbranch_vccnz .LBB0_768
	v_mov_b32_e32 v20, v15
	v_mov_b32_e32 v21, v11
	v_mov_b32_e32 v18, v14
	v_mov_b32_e32 v19, v10
	v_pk_mul_f32 v[20:21], v[20:21], v[20:21]
	v_mov_b32_e32 v22, v17
	v_mov_b32_e32 v23, v13
	v_pk_fma_f32 v[18:19], v[18:19], v[18:19], v[20:21]
	v_mov_b32_e32 v20, v16
	v_mov_b32_e32 v21, v12
	v_pk_mul_f32 v[22:23], v[22:23], v[22:23]
	v_pk_mul_f32 v[26:27], v[68:69], v[12:13]
	v_pk_fma_f32 v[20:21], v[20:21], v[20:21], v[22:23]
	v_pk_mul_f32 v[22:23], v[70:71], v[14:15]
	v_pk_add_f32 v[18:19], v[18:19], v[20:21]
	v_pk_mul_f32 v[24:25], v[66:67], v[10:11]
	v_add_f32_e32 v20, v18, v19
	v_pk_mul_f32 v[18:19], v[72:73], v[16:17]
	v_cvt_pk_bf16_f32 v22, v22, v23
	v_cvt_pk_bf16_f32 v23, v18, v19
	v_cvt_pk_bf16_f32 v24, v24, v25
	v_cvt_pk_bf16_f32 v25, v26, v27
	s_mov_b64 s[20:21], 0
	global_store_dwordx4 v[46:47], v[22:25], off

.LBB0_770:
	s_waitcnt vmcnt(0)
	s_nop 0
	v_lshlrev_b32_e32 v10, 16, v126
	v_and_b32_e32 v11, 0xffff0000, v126
	v_lshlrev_b32_e32 v12, 16, v127
	v_and_b32_e32 v13, 0xffff0000, v127
	v_lshlrev_b32_e32 v14, 16, v128
	v_and_b32_e32 v15, 0xffff0000, v128
	v_lshlrev_b32_e32 v16, 16, v129
	v_and_b32_e32 v17, 0xffff0000, v129
	v_pk_mul_f32 v[10:11], v[82:83], v[10:11]
	v_pk_mul_f32 v[12:13], v[84:85], v[12:13]
	v_pk_mul_f32 v[14:15], v[86:87], v[14:15]
	v_pk_mul_f32 v[16:17], v[88:89], v[16:17]
	v_pk_fma_f32 v[8:9], v[8:9], v[158:159], v[12:13]
	v_pk_fma_f32 v[6:7], v[6:7], v[160:161], v[10:11]
	v_pk_fma_f32 v[4:5], v[4:5], v[154:155], v[16:17]
	v_pk_fma_f32 v[2:3], v[2:3], v[156:157], v[14:15]
	s_and_b64 vcc, exec, s[6:7]
	s_mov_b64 s[20:21], -1
	s_cbranch_vccnz .LBB0_776
	v_mov_b32_e32 v12, v7
	v_mov_b32_e32 v13, v3
	v_mov_b32_e32 v10, v6
	v_mov_b32_e32 v11, v2
	v_pk_mul_f32 v[12:13], v[12:13], v[12:13]
	v_mov_b32_e32 v14, v9
	v_mov_b32_e32 v15, v5
	v_pk_fma_f32 v[10:11], v[10:11], v[10:11], v[12:13]
	v_mov_b32_e32 v12, v8
	v_mov_b32_e32 v13, v4
	v_pk_mul_f32 v[14:15], v[14:15], v[14:15]
	v_pk_mul_f32 v[16:17], v[60:61], v[4:5]
	v_pk_fma_f32 v[12:13], v[12:13], v[12:13], v[14:15]
	v_pk_mul_f32 v[14:15], v[64:65], v[8:9]
	v_pk_add_f32 v[10:11], v[10:11], v[12:13]
	v_pk_mul_f32 v[12:13], v[62:63], v[6:7]
	v_add_f32_e32 v10, v10, v11
	v_pk_mul_f32 v[22:23], v[58:59], v[2:3]
	v_add_f32_e32 v10, v10, v20
	v_cvt_pk_bf16_f32 v12, v12, v13
	v_cvt_pk_bf16_f32 v13, v14, v15
	v_cvt_pk_bf16_f32 v14, v22, v23
	v_cvt_pk_bf16_f32 v15, v16, v17
	global_store_dwordx4 v[46:47], v[12:15], off offset:256
	s_cbranch_execz .LBB0_777
